# NSA phase A: the 64 CU-mates of the compress-GEMM workgroups take no window units (redistributed over the other 384 workgroups)
# speedup vs baseline: 1.0156x; 1.0048x over previous
; __global__ void __launch_bounds__(256, 2) mega_kernel(Params p) {
;     ...
;       if (G == 512) { if (blockIdx.x >= 64) for (int u = blockIdx.x - 64; u < 2048; u += 448) nsa_win_unit(p, u, smem); }
;       else for (int u = blockIdx.x; u < 2048; u += G) nsa_win_unit(p, u, smem);
.Lqbflip_skip:
	v_writelane_b32 v230, s3, 28
	s_lshl_b32 s3, s69, 3
	s_xor_b32 s3, s3, 0xf8
	s_mul_i32 s6, s3, 0x843
	s_addk_i32 s6, 0x7bed
	v_writelane_b32 v230, s34, 29
	s_lshr_b32 s6, s6, 16
	s_cmp_gt_u32 s3, 15
	v_writelane_b32 v230, s35, 30
	v_writelane_b32 v230, s6, 31
	s_cselect_b64 s[34:35], -1, 0
	v_writelane_b32 v230, s34, 32
	s_and_b32 s3, s28, 0x7fffff80
	s_addk_i32 s3, 0x800
	v_writelane_b32 v230, s35, 33
	v_writelane_b32 v230, s28, 34
	v_writelane_b32 v230, s3, 35
	s_add_u32 s3, s26, 0x1000000
	v_writelane_b32 v230, s3, 36
	s_addc_u32 s3, s27, 0
	s_cmpk_lt_u32 s86, 0x400
	v_writelane_b32 v230, s3, 37
	s_cselect_b64 s[28:29], -1, 0
	s_lshl_b32 s70, s2, 10
	s_movk_i32 s2, 0x800
	v_writelane_b32 v230, s28, 38
	s_cmp_eq_u64 s[18:19], 0
	v_cmp_gt_i32_e32 vcc, s2, v2
	v_writelane_b32 v230, s29, 39
	s_cselect_b64 s[2:3], -1, 0
	s_and_b64 s[0:1], s[0:1], vcc
	s_cmpk_lt_u32 s86, 0x100
	s_cbranch_scc1 .Lwb_skip
	s_cmpk_ge_u32 s86, 0x140
	s_cbranch_scc1 .Lwb_skip
	s_mov_b64 s[0:1], 0
.Lwb_skip:
	v_writelane_b32 v230, s0, 40
	v_mov_b32_e32 v204, 0xff800000
	v_not_b32_e32 v205, 32
	v_writelane_b32 v230, s1, 41
	v_writelane_b32 v230, s30, 42
	s_and_b64 s[0:1], s[30:31], s[4:5]
	s_load_dwordx2 s[4:5], s[80:81], 0x0
	v_writelane_b32 v230, s31, 43
	v_writelane_b32 v230, s0, 44
	v_mbcnt_hi_u32_b32 v202, -1, v10
	v_mov_b32_e32 v206, 0xf149f2ca
	v_writelane_b32 v230, s1, 45
	s_and_b32 s0, s69, 30
	s_cmp_lg_u32 s69, s0
	v_writelane_b32 v230, s0, 46
	s_cselect_b64 s[0:1], -1, 0
	v_writelane_b32 v230, s0, 47
	v_mov_b32_e32 v207, 0x3f80
	v_mov_b32_e32 v208, 0x3f00
	v_writelane_b32 v230, s1, 48
	s_abs_i32 s0, s82
	v_cvt_f32_u32_e32 v0, s0
	v_writelane_b32 v230, s0, 49
	s_sub_i32 s0, 0, s0
	s_mov_b32 s34, 0x3fb8aa3b
	v_rcp_iflag_f32_e32 v0, v0
	s_mov_b32 s35, 0xff800000
	s_mov_b32 s60, 0xf0c9f2ca
	s_mov_b32 s61, 0x5040100
	v_mul_f32_e32 v0, 0x4f7ffffe, v0
	v_cvt_u32_f32_e32 v0, v0
	s_mov_b64 s[88:89], 0x200000
	s_mov_b64 s[92:93], 0x400000
	s_mov_b64 s[84:85], 0x402000
	v_readfirstlane_b32 s1, v0
	s_mul_i32 s0, s0, s1
	s_mul_hi_u32 s0, s1, s0
	s_add_i32 s0, s1, s0
	v_writelane_b32 v230, s0, 50
	v_writelane_b32 v230, s36, 51
	s_ashr_i32 s0, s82, 31
	v_lshrrev_b32_e32 v0, 2, v167
	v_writelane_b32 v229, s49, 0
	v_writelane_b32 v229, s50, 1
	v_writelane_b32 v229, s51, 2
	v_writelane_b32 v229, s10, 3
	v_writelane_b32 v230, s37, 52
	v_writelane_b32 v230, s38, 53
	v_writelane_b32 v229, s11, 4
	v_writelane_b32 v229, s0, 5
	s_lshl_b32 s0, s90, 5
	v_writelane_b32 v229, s0, 6
	s_lshl_b32 s0, s71, 5
	v_writelane_b32 v229, s0, 7
	s_add_u32 s0, s22, 0x400000
	s_addc_u32 s1, s23, 0
	v_writelane_b32 v229, s0, 8
	s_add_u32 s77, s80, 0x160
	s_addc_u32 s76, s81, 0
	v_writelane_b32 v229, s1, 9
	v_readfirstlane_b32 s0, v2
	s_cmpk_lt_u32 s86, 0x140
	s_cbranch_scc1 .Lwa_skip
	s_sub_i32 s0, s0, 64
.Lwa_skip:
	s_mov_b32 s1, 0
	s_xor_b64 s[72:73], s[2:3], -1
	v_writelane_b32 v229, s0, 10
	s_lshl_b32 s0, s86, 7
	v_writelane_b32 v229, s0, 11
	s_lshl_b32 s0, s82, 7
	v_writelane_b32 v229, s0, 12
	s_lshl_b32 s0, s86, 8
	v_writelane_b32 v229, s0, 13
	s_lshl_b32 s0, s82, 8
	v_writelane_b32 v229, s0, 14
	s_add_i32 s0, 0, 0xd000
	v_writelane_b32 v229, s0, 15
	v_writelane_b32 v229, s1, 16
	v_cmp_eq_u32_e64 s[2:3], 0, v167
	v_writelane_b32 v230, s39, 54
	v_writelane_b32 v230, s40, 55
	v_writelane_b32 v229, s2, 17
	v_writelane_b32 v230, s41, 56
	v_writelane_b32 v230, s42, 57
	v_writelane_b32 v229, s3, 18
	s_load_dwordx2 s[2:3], s[80:81], 0x150
	v_writelane_b32 v230, s43, 58
	v_writelane_b32 v230, s44, 59
	v_and_b32_e32 v166, 8, v0
	v_lshlrev_b32_e32 v0, 3, v167
	s_waitcnt lgkmcnt(0)
	v_writelane_b32 v229, s2, 19
	v_writelane_b32 v230, s45, 60
	v_and_b32_e32 v168, 56, v0
	v_writelane_b32 v229, s3, 20
	s_lshl_b64 s[2:3], s[86:87], 11
	v_writelane_b32 v229, s2, 21
	v_lshlrev_b32_e32 v0, 13, v169
	v_writelane_b32 v230, s46, 61
	v_writelane_b32 v229, s3, 22
	v_writelane_b32 v229, s4, 23
	v_writelane_b32 v230, s47, 62
	v_lshl_add_u64 v[172:173], s[36:37], 0, v[0:1]
	v_writelane_b32 v229, s5, 24
	s_load_dwordx4 s[4:7], s[80:81], 0x30
	v_mul_u32_u24_e32 v0, 0x48, v169
	v_writelane_b32 v230, s48, 63
	s_mov_b64 s[48:49], s[8:9]
	v_lshlrev_b32_e32 v0, 1, v0
	s_waitcnt lgkmcnt(0)
	v_writelane_b32 v229, s4, 25
	v_lshlrev_b32_e32 v3, 1, v168
	v_add3_u32 v175, 0, v0, v3
	v_writelane_b32 v229, s5, 26
	v_writelane_b32 v229, s6, 27
	v_writelane_b32 v229, s7, 28
	v_writelane_b32 v229, s12, 29
	v_and_b32_e32 v0, 31, v167
	v_bfe_u32 v3, v167, 5, 1
	v_writelane_b32 v229, s13, 30
	v_writelane_b32 v229, s14, 31
	v_writelane_b32 v229, s15, 32
	v_writelane_b32 v229, s16, 33
	v_writelane_b32 v229, s17, 34
	v_writelane_b32 v229, s18, 35
	v_writelane_b32 v229, s19, 36
	v_writelane_b32 v229, s20, 37
	v_writelane_b32 v229, s21, 38
	v_writelane_b32 v229, s22, 39
	v_writelane_b32 v229, s23, 40
	v_writelane_b32 v229, s24, 41
	v_writelane_b32 v229, s25, 42
	v_writelane_b32 v229, s26, 43
	v_writelane_b32 v229, s27, 44
	v_writelane_b32 v229, s69, 45
	v_writelane_b32 v229, s70, 46
	v_writelane_b32 v229, s72, 47
	v_mul_u32_u24_e32 v0, 0x48, v0
	s_lshl_b64 s[2:3], s[82:83], 11
	v_writelane_b32 v229, s73, 48
	v_writelane_b32 v229, s96, 49
	v_lshlrev_b32_e32 v4, 3, v3
	v_lshl_add_u32 v177, v3, 4, 0
	v_writelane_b32 v229, s97, 50
	v_writelane_b32 v229, s48, 51
	v_lshlrev_b32_e32 v0, 1, v0
	v_add_u32_e32 v196, v177, v0
	v_writelane_b32 v229, s49, 52
	v_writelane_b32 v229, s2, 53
	v_add3_u32 v198, 0, v0, v4
	v_lshlrev_b32_e32 v0, 1, v174
	v_writelane_b32 v229, s3, 54
	v_lshlrev_b32_e32 v197, 2, v3
	v_add_u32_e32 v199, v198, v4
	v_sub_u32_e32 v200, 0, v4
	v_lshl_add_u64 v[178:179], s[10:11], 0, v[0:1]
	s_movk_i32 s0, 0x110
	s_mov_b64 s[52:53], 0x403000
	s_mov_b64 s[56:57], 0x10000
	s_mov_b32 s50, s59
	v_writelane_b32 v229, s74, 55
	s_barrier
	s_nop 0
	v_writelane_b32 v229, s75, 56
	s_branch .LBB0_82

; DI void nsa_win_unit(const Params& p, int u, char* smem) {
;     ...
;   l += __shfl_xor(l, 32);
;   store_plain(o, 1.f / l, p.Q + (size_t)2 * NTOK * 1024 + tok * 1024 + head * 64);
; __global__ void __launch_bounds__(256, 2) mega_kernel(Params p) {
;     ...
;       if (G == 512) { if (blockIdx.x >= 64) for (int u = blockIdx.x - 64; u < 2048; u += 448) nsa_win_unit(p, u, smem); }
.LBB0_585:
	v_and_b32_e32 v34, 64, v202
	v_xor_b32_e32 v0, 32, v202
	v_add_u32_e32 v34, 64, v34
	v_cmp_lt_i32_e32 vcc, v0, v34
	v_lshl_add_u64 v[34:35], v[146:147], 1, s[44:45]
	v_lshl_add_u64 v[34:35], s[2:3], 1, v[34:35]
	v_cndmask_b32_e32 v0, v202, v0, vcc
	v_lshlrev_b32_e32 v0, 2, v0
	ds_bpermute_b32 v0, v0, v159
	s_add_i32 s2, s1, 0x180
	s_cmpk_gt_i32 s1, 0x67f
	s_mov_b32 s1, s2
	s_waitcnt lgkmcnt(0)
	v_add_f32_e32 v0, v159, v0
	v_div_scale_f32 v36, s[4:5], v0, v0, 1.0
	v_rcp_f32_e32 v37, v36
	v_div_scale_f32 v38, vcc, 1.0, v0, 1.0
	v_fma_f32 v39, -v36, v37, 1.0
	v_fmac_f32_e32 v37, v39, v37
	v_mul_f32_e32 v39, v38, v37
	v_fma_f32 v40, -v36, v39, v38
	v_fmac_f32_e32 v39, v40, v37
	v_fma_f32 v36, -v36, v39, v38
	v_div_fmas_f32 v36, v36, v37, v39
	v_div_fixup_f32 v36, v36, v0, 1.0
	v_lshlrev_b32_e32 v0, 1, v174
	v_pk_mul_f32 v[2:3], v[2:3], v[36:37] op_sel_hi:[1,0]
	v_pk_mul_f32 v[4:5], v[4:5], v[36:37] op_sel_hi:[1,0]
	v_lshl_add_u64 v[34:35], v[34:35], 0, v[0:1]
	v_cvt_pk_bf16_f32 v2, v2, v3
	v_cvt_pk_bf16_f32 v3, v4, v5
	global_store_dwordx2 v[34:35], v[2:3], off
	v_pk_mul_f32 v[2:3], v[6:7], v[36:37] op_sel_hi:[1,0]
	v_pk_mul_f32 v[4:5], v[8:9], v[36:37] op_sel_hi:[1,0]
	v_cvt_pk_bf16_f32 v2, v2, v3
	v_cvt_pk_bf16_f32 v3, v4, v5
	global_store_dwordx2 v[34:35], v[2:3], off offset:16
	v_pk_mul_f32 v[2:3], v[10:11], v[36:37] op_sel_hi:[1,0]
	v_pk_mul_f32 v[4:5], v[12:13], v[36:37] op_sel_hi:[1,0]
	v_cvt_pk_bf16_f32 v2, v2, v3
	v_cvt_pk_bf16_f32 v3, v4, v5
	global_store_dwordx2 v[34:35], v[2:3], off offset:32
	v_pk_mul_f32 v[2:3], v[14:15], v[36:37] op_sel_hi:[1,0]
	v_pk_mul_f32 v[4:5], v[16:17], v[36:37] op_sel_hi:[1,0]
	v_cvt_pk_bf16_f32 v2, v2, v3
	v_cvt_pk_bf16_f32 v3, v4, v5
	global_store_dwordx2 v[34:35], v[2:3], off offset:48
	v_pk_mul_f32 v[2:3], v[18:19], v[36:37] op_sel_hi:[1,0]
	v_pk_mul_f32 v[4:5], v[20:21], v[36:37] op_sel_hi:[1,0]
	v_cvt_pk_bf16_f32 v2, v2, v3
	v_cvt_pk_bf16_f32 v3, v4, v5
	global_store_dwordx2 v[34:35], v[2:3], off offset:64
	v_pk_mul_f32 v[2:3], v[22:23], v[36:37] op_sel_hi:[1,0]
	v_pk_mul_f32 v[4:5], v[24:25], v[36:37] op_sel_hi:[1,0]
	v_cvt_pk_bf16_f32 v2, v2, v3
	v_cvt_pk_bf16_f32 v3, v4, v5
	global_store_dwordx2 v[34:35], v[2:3], off offset:80
	v_pk_mul_f32 v[2:3], v[26:27], v[36:37] op_sel_hi:[1,0]
	v_pk_mul_f32 v[4:5], v[28:29], v[36:37] op_sel_hi:[1,0]
	v_cvt_pk_bf16_f32 v2, v2, v3
	v_cvt_pk_bf16_f32 v3, v4, v5
	global_store_dwordx2 v[34:35], v[2:3], off offset:96
	v_pk_mul_f32 v[2:3], v[30:31], v[36:37] op_sel_hi:[1,0]
	v_pk_mul_f32 v[4:5], v[32:33], v[36:37] op_sel_hi:[1,0]
	v_cvt_pk_bf16_f32 v2, v2, v3
	v_cvt_pk_bf16_f32 v3, v4, v5
	global_store_dwordx2 v[34:35], v[2:3], off offset:112
	s_cbranch_scc1 .LBB0_347
